# attention-B QK block: counted lgkmcnt waits (one K fragment per MFMA) instead of a full drain of the second K batch before the 4th MFMA
# speedup vs baseline: 1.0021x; 1.0021x over previous
; #define SBAR() __builtin_amdgcn_sched_barrier(0)
; __device__ __forceinline__ void finishSM2T(f32x16& p0, f32x16& p1, float& l_reg, bf16x8& pa0, bf16x8& pa1, bf16x8& pa2, bf16x8& pa3) {
; #pragma unroll
;     for (int r = 0; r < 16; ++r) p1[r] = __builtin_amdgcn_exp2f(p1[r]);
;     { float ps = 0.f;
; #pragma unroll
;       for (int r = 0; r < 16; ++r) ps += p0[r];
; #pragma unroll
;       for (int r = 0; r < 16; ++r) ps += p1[r];
;       auto rr = __builtin_amdgcn_permlane32_swap(__float_as_uint(ps), __float_as_uint(ps), false, false);
;       l_reg += __uint_as_float(rr[0]) + __uint_as_float(rr[1]); }
; template <int ROWB> __device__ __forceinline__ void qkt64n(f32x16& p0, f32x16& p1, const char* Ks, const bf16x8* qr, int r32, int hi, int colb0, const f32x16& negm) {
;     const char* k0 = Ks + r32 * ROWB; const char* k1 = Ks + (32 + r32) * ROWB; const int sw = (r32 & 7) << 4;
;     ...
;     const bf16x8 a0 = *reinterpret_cast<const bf16x8*>(k0 + KCB(0)), a1 = *reinterpret_cast<const bf16x8*>(k1 + KCB(0));
;     const bf16x8 c0 = *reinterpret_cast<const bf16x8*>(k0 + KCB(1)), c1 = *reinterpret_cast<const bf16x8*>(k1 + KCB(1));
;     asm volatile("s_waitcnt lgkmcnt(0)" ::: "memory"); SBAR();
;     p0 = __builtin_amdgcn_mfma_f32_32x32x16_bf16(a0, qr[0], negm, 0, 0, 0); p1 = __builtin_amdgcn_mfma_f32_32x32x16_bf16(a1, qr[0], negm, 0, 0, 0);
;     const bf16x8 e0 = *reinterpret_cast<const bf16x8*>(k0 + KCB(2)), e1 = *reinterpret_cast<const bf16x8*>(k1 + KCB(2));
;     const bf16x8 g0 = *reinterpret_cast<const bf16x8*>(k0 + KCB(3)), g1 = *reinterpret_cast<const bf16x8*>(k1 + KCB(3));
;     p0 = __builtin_amdgcn_mfma_f32_32x32x16_bf16(c0, qr[1], p0, 0, 0, 0); p1 = __builtin_amdgcn_mfma_f32_32x32x16_bf16(c1, qr[1], p1, 0, 0, 0);
;     asm volatile("s_waitcnt lgkmcnt(0)" ::: "memory"); SBAR();
;     p0 = __builtin_amdgcn_mfma_f32_32x32x16_bf16(e0, qr[2], p0, 0, 0, 0); p1 = __builtin_amdgcn_mfma_f32_32x32x16_bf16(e1, qr[2], p1, 0, 0, 0);
;     p0 = __builtin_amdgcn_mfma_f32_32x32x16_bf16(g0, qr[3], p0, 0, 0, 0); p1 = __builtin_amdgcn_mfma_f32_32x32x16_bf16(g1, qr[3], p1, 0, 0, 0);
.LBB0_273:
	s_add_i32 s4, s49, s48
	v_lshl_add_u64 v[2:3], v[168:169], 0, s[0:1]
	s_add_i32 m0, s4, 0xc000
	v_lshl_add_u64 v[8:9], v[2:3], 0, s[44:45]
	global_load_lds_dwordx4 v[8:9], off
	v_lshl_add_u64 v[8:9], v[170:171], 0, s[0:1]
	v_lshl_add_u64 v[10:11], v[8:9], 0, s[44:45]
	s_add_i32 m0, s4, 0xe000
	s_nop 0
	global_load_lds_dwordx4 v[10:11], off
	v_add_u32_e32 v1, s53, v194
	v_add_u32_e32 v14, v1, v192
	ds_read_b128 v[10:13], v14
	ds_read_b128 v[220:223], v14 offset:8192
	v_add_u32_e32 v14, v1, v193
	ds_read_b128 v[224:227], v14
	ds_read_b128 v[228:231], v14 offset:8192
	v_add_u32_e32 v254, s51, v189
	ds_read_b64_tr_b16 v[236:237], v254 offset:0x0
	ds_read_b64_tr_b16 v[238:239], v254 offset:0x800
	ds_read_b64_tr_b16 v[240:241], v254 offset:0x200
	ds_read_b64_tr_b16 v[242:243], v254 offset:0xa00
	ds_read_b64_tr_b16 v[246:247], v254 offset:0x400
	ds_read_b64_tr_b16 v[248:249], v254 offset:0xc00
	ds_read_b64_tr_b16 v[250:251], v254 offset:0x600
	ds_read_b64_tr_b16 v[252:253], v254 offset:0xe00
	s_waitcnt lgkmcnt(8)
	s_waitcnt lgkmcnt(8)
	v_mfma_f32_32x32x16_bf16 v[130:145], v[10:13], v[158:161], v[82:97]
	v_add_u32_e32 v14, v1, v190
	v_add_u32_e32 v1, v1, v195
	v_mfma_f32_32x32x16_bf16 v[114:129], v[220:223], v[158:161], v[82:97]
	ds_read_b128 v[10:13], v14
	ds_read_b128 v[220:223], v14 offset:8192
	v_mfma_f32_32x32x16_bf16 v[130:145], v[224:227], v[154:157], v[130:145]
	ds_read_b128 v[224:227], v1
	ds_read_b128 v[232:235], v1 offset:8192
	s_waitcnt lgkmcnt(12)
	v_mfma_f32_32x32x16_bf16 v[114:129], v[228:231], v[154:157], v[114:129]
	s_waitcnt lgkmcnt(3)
	v_mfma_f32_32x32x16_bf16 v[130:145], v[10:13], v[150:153], v[130:145]
	v_add_f32_e32 v11, 0, v212
	v_add_f32_e32 v11, v216, v11
	v_add_f32_e32 v11, v213, v11
	v_add_f32_e32 v11, v217, v11
	v_add_f32_e32 v11, v214, v11
	v_add_f32_e32 v11, v218, v11
	v_add_f32_e32 v11, v215, v11
	v_add_f32_e32 v11, v219, v11
	v_add_f32_e32 v11, v197, v11
	v_add_f32_e32 v11, v208, v11
	v_add_f32_e32 v11, v198, v11
	v_add_f32_e32 v11, v209, v11
	v_exp_f32_e32 v1, v98
	v_add_f32_e32 v11, v199, v11
	v_exp_f32_e32 v10, v99
	v_add_f32_e32 v11, v210, v11
	v_exp_f32_e32 v13, v100
	v_add_f32_e32 v11, v207, v11
	v_exp_f32_e32 v14, v101
	v_add_f32_e32 v11, v211, v11
	v_exp_f32_e32 v15, v102
	v_add_f32_e32 v11, v1, v11
	s_waitcnt lgkmcnt(2)
	v_mfma_f32_32x32x16_bf16 v[114:129], v[220:223], v[150:153], v[114:129]
	v_exp_f32_e32 v220, v103
	v_add_f32_e32 v11, v10, v11
	v_exp_f32_e32 v221, v104
	v_add_f32_e32 v11, v13, v11
	v_exp_f32_e32 v222, v105
	v_add_f32_e32 v11, v14, v11
	v_exp_f32_e32 v223, v106
	v_add_f32_e32 v11, v15, v11
	s_waitcnt lgkmcnt(1)
	v_mfma_f32_32x32x16_bf16 v[130:145], v[224:227], v[146:149], v[130:145]
	v_exp_f32_e32 v224, v107
	v_add_f32_e32 v11, v220, v11
	v_exp_f32_e32 v225, v108
	v_add_f32_e32 v11, v221, v11
	v_exp_f32_e32 v226, v109
	v_add_f32_e32 v11, v222, v11
	v_exp_f32_e32 v227, v110
	v_add_f32_e32 v11, v223, v11
	v_exp_f32_e32 v228, v111
	v_add_f32_e32 v11, v224, v11
	s_waitcnt lgkmcnt(0)
; #define SBAR() __builtin_amdgcn_sched_barrier(0)
; #define PK8(P, BASE, OUT) do { u32x4 w = {cvtpk(P[BASE + 0], P[BASE + 1]), cvtpk(P[BASE + 2], P[BASE + 3]), cvtpk(P[BASE + 4], P[BASE + 5]), cvtpk(P[BASE + 6], P[BASE + 7])}; OUT = *reinterpret_cast<bf16x8*>(&w); } while (0)
; __device__ __forceinline__ void finishSM2T(f32x16& p0, f32x16& p1, float& l_reg, bf16x8& pa0, bf16x8& pa1, bf16x8& pa2, bf16x8& pa3) {
;     ...
;     PK8(p0, 0, pa0); PK8(p0, 8, pa1); PK8(p1, 0, pa2); PK8(p1, 8, pa3);
;     ...
; }
; template <int KS> __device__ __forceinline__ void pv_ksT(f32x16* o, int vb, bf16x8 pa) {
;     const s16x4 l0 = tr_read<v_rd_off<4>(0, KS, 0)>(vb), h0 = tr_read<v_rd_off<4>(0, KS, 1)>(vb), l1 = tr_read<v_rd_off<4>(1, KS, 0)>(vb), h1 = tr_read<v_rd_off<4>(1, KS, 1)>(vb);
;     const s16x4 l2 = tr_read<v_rd_off<4>(2, KS, 0)>(vb), h2 = tr_read<v_rd_off<4>(2, KS, 1)>(vb), l3 = tr_read<v_rd_off<4>(3, KS, 0)>(vb), h3 = tr_read<v_rd_off<4>(3, KS, 1)>(vb);
;     asm volatile("s_waitcnt lgkmcnt(0)" ::: "memory"); SBAR();
;     ...
;     o[0] = __builtin_amdgcn_mfma_f32_32x32x16_bf16(PKV(l0, h0), pa, o[0], 0, 0, 0);
;     o[1] = __builtin_amdgcn_mfma_f32_32x32x16_bf16(PKV(l1, h1), pa, o[1], 0, 0, 0);
;     o[2] = __builtin_amdgcn_mfma_f32_32x32x16_bf16(PKV(l2, h2), pa, o[2], 0, 0, 0);
;     o[3] = __builtin_amdgcn_mfma_f32_32x32x16_bf16(PKV(l3, h3), pa, o[3], 0, 0, 0);
;     ...
; }
; template <bool FIRST> __device__ __forceinline__ void partialSM2(f32x16& p0, f32x16& p1, float& m_ref, float& alpha, f32x16& negm) {
;     float pmax = p0[0];
; #pragma unroll
;     for (int r = 1; r < 16; ++r) pmax = fmaxf(pmax, p0[r]);
; #pragma unroll
;     for (int r = 0; r < 16; ++r) pmax = fmaxf(pmax, p1[r]);
;     { auto rr = __builtin_amdgcn_permlane32_swap(__float_as_uint(pmax), __float_as_uint(pmax), false, false);
;       pmax = fmaxf(__uint_as_float(rr[0]), __uint_as_float(rr[1])); }
;     alpha = 1.f;
;     if (FIRST || !__builtin_expect(__all(pmax <= ATT_THR), 1)) {
	v_mfma_f32_32x32x16_bf16 v[114:129], v[232:235], v[146:149], v[114:129]
	v_exp_f32_e32 v229, v112
	v_add_f32_e32 v11, v225, v11
	v_exp_f32_e32 v113, v113
	v_add_f32_e32 v11, v226, v11
	v_add_f32_e32 v11, v227, v11
	v_add_f32_e32 v11, v228, v11
	v_add_f32_e32 v11, v229, v11
	v_add_f32_e32 v11, v113, v11
	v_mov_b32_e32 v12, v11
	s_nop 1
	v_permlane32_swap_b32_e32 v11, v12
	v_cvt_pk_bf16_f32 v98, v212, v216
	v_cvt_pk_bf16_f32 v99, v213, v217
	v_cvt_pk_bf16_f32 v100, v214, v218
	v_cvt_pk_bf16_f32 v101, v215, v219
	v_cvt_pk_bf16_f32 v102, v197, v208
	v_cvt_pk_bf16_f32 v103, v198, v209
	v_cvt_pk_bf16_f32 v104, v199, v210
	v_cvt_pk_bf16_f32 v105, v207, v211
	v_cvt_pk_bf16_f32 v106, v1, v10
	v_cvt_pk_bf16_f32 v107, v13, v14
	v_cvt_pk_bf16_f32 v108, v15, v220
	v_cvt_pk_bf16_f32 v109, v221, v222
	v_cvt_pk_bf16_f32 v110, v223, v224
	v_cvt_pk_bf16_f32 v111, v225, v226
	v_cvt_pk_bf16_f32 v112, v227, v228
	v_cvt_pk_bf16_f32 v113, v229, v113
	v_add_u32_e32 v1, s51, v189
	ds_read_b64_tr_b16 v[208:209], v254 offset:0x1000
	ds_read_b64_tr_b16 v[210:211], v254 offset:0x1800
	ds_read_b64_tr_b16 v[212:213], v254 offset:0x1200
	ds_read_b64_tr_b16 v[214:215], v254 offset:0x1a00
	ds_read_b64_tr_b16 v[216:217], v254 offset:0x1400
	ds_read_b64_tr_b16 v[218:219], v254 offset:0x1c00
	ds_read_b64_tr_b16 v[220:221], v254 offset:0x1600
	ds_read_b64_tr_b16 v[222:223], v254 offset:0x1e00
	s_waitcnt lgkmcnt(8)
	s_nop 0
	v_mfma_f32_32x32x16_bf16 v[66:81], v[236:239], v[98:101], v[66:81]
	v_mfma_f32_32x32x16_bf16 v[50:65], v[240:243], v[98:101], v[50:65]
	v_mfma_f32_32x32x16_bf16 v[34:49], v[246:249], v[98:101], v[34:49]
	v_mfma_f32_32x32x16_bf16 v[18:33], v[250:253], v[98:101], v[18:33]
	ds_read_b64_tr_b16 v[236:237], v254 offset:0x2000
	ds_read_b64_tr_b16 v[238:239], v254 offset:0x2800
	ds_read_b64_tr_b16 v[240:241], v254 offset:0x2200
	ds_read_b64_tr_b16 v[242:243], v254 offset:0x2a00
	ds_read_b64_tr_b16 v[246:247], v254 offset:0x2400
	ds_read_b64_tr_b16 v[248:249], v254 offset:0x2c00
	ds_read_b64_tr_b16 v[250:251], v254 offset:0x2600
	ds_read_b64_tr_b16 v[252:253], v254 offset:0x2e00
	s_waitcnt lgkmcnt(8)
	s_nop 0
	v_mfma_f32_32x32x16_bf16 v[66:81], v[208:211], v[102:105], v[66:81]
	v_mfma_f32_32x32x16_bf16 v[50:65], v[212:215], v[102:105], v[50:65]
	v_mfma_f32_32x32x16_bf16 v[34:49], v[216:219], v[102:105], v[34:49]
	v_mfma_f32_32x32x16_bf16 v[18:33], v[220:223], v[102:105], v[18:33]
	ds_read_b64_tr_b16 v[208:209], v254 offset:0x3000
	ds_read_b64_tr_b16 v[210:211], v254 offset:0x3800
	ds_read_b64_tr_b16 v[212:213], v254 offset:0x3200
	ds_read_b64_tr_b16 v[214:215], v254 offset:0x3a00
	ds_read_b64_tr_b16 v[216:217], v254 offset:0x3400
	ds_read_b64_tr_b16 v[218:219], v254 offset:0x3c00
	ds_read_b64_tr_b16 v[220:221], v254 offset:0x3600
	ds_read_b64_tr_b16 v[222:223], v254 offset:0x3e00
	s_waitcnt lgkmcnt(8)
	s_nop 0
	v_mfma_f32_32x32x16_bf16 v[66:81], v[236:239], v[106:109], v[66:81]
	v_mfma_f32_32x32x16_bf16 v[50:65], v[240:243], v[106:109], v[50:65]
	v_mfma_f32_32x32x16_bf16 v[34:49], v[246:249], v[106:109], v[34:49]
	v_mfma_f32_32x32x16_bf16 v[18:33], v[250:253], v[106:109], v[18:33]
	s_waitcnt lgkmcnt(0)
	v_max_f32_e32 v10, v131, v131
	v_max_f32_e32 v13, v130, v130
	v_max_f32_e32 v10, v13, v10
	v_max3_f32 v10, v10, v132, v133
	v_max3_f32 v10, v10, v134, v135
	v_max3_f32 v10, v10, v136, v137
	v_max3_f32 v10, v10, v138, v139
	v_max3_f32 v10, v10, v140, v141
	v_max3_f32 v10, v10, v142, v143
	v_max3_f32 v10, v10, v144, v145
	v_max3_f32 v10, v10, v114, v115
	v_max3_f32 v10, v10, v116, v117
	v_max3_f32 v10, v10, v118, v119
	v_max3_f32 v10, v10, v120, v121
	v_max3_f32 v10, v10, v122, v123
	v_max3_f32 v10, v10, v124, v125
	v_mfma_f32_32x32x16_bf16 v[66:81], v[208:211], v[110:113], v[66:81]
	v_max3_f32 v10, v10, v126, v127
	v_max3_f32 v10, v10, v128, v129
	v_mov_b32_e32 v13, v10
	s_nop 1
	v_permlane32_swap_b32_e32 v10, v13
	v_max_f32_e32 v13, v13, v13
	v_max_f32_e32 v10, v10, v10
	v_mfma_f32_32x32x16_bf16 v[50:65], v[212:215], v[110:113], v[50:65]
	v_max_f32_e32 v13, v10, v13
	v_cmp_ge_f32_e32 vcc, s68, v13
	s_cmp_eq_u64 vcc, exec
	v_mov_b32_e32 v10, 1.0
	v_mfma_f32_32x32x16_bf16 v[34:49], v[216:219], v[110:113], v[34:49]
	v_mfma_f32_32x32x16_bf16 v[18:33], v[220:223], v[110:113], v[18:33]
	s_cbranch_scc0 .LBB0_297
	v_add_f32_e32 v11, v11, v12
	v_add_f32_e32 v11, v196, v11
	v_cmp_gt_f32_e32 vcc, 1.0, v10
	s_cbranch_vccz .LBB0_276

; #define SBAR() __builtin_amdgcn_sched_barrier(0)
; __device__ __forceinline__ void finishSM2T(f32x16& p0, f32x16& p1, float& l_reg, bf16x8& pa0, bf16x8& pa1, bf16x8& pa2, bf16x8& pa3) {
; #pragma unroll
;     for (int r = 0; r < 16; ++r) p1[r] = __builtin_amdgcn_exp2f(p1[r]);
;     { float ps = 0.f;
; #pragma unroll
;       for (int r = 0; r < 16; ++r) ps += p0[r];
; #pragma unroll
;       for (int r = 0; r < 16; ++r) ps += p1[r];
;       auto rr = __builtin_amdgcn_permlane32_swap(__float_as_uint(ps), __float_as_uint(ps), false, false);
;       l_reg += __uint_as_float(rr[0]) + __uint_as_float(rr[1]); }
; template <int ROWB> __device__ __forceinline__ void qkt64n(f32x16& p0, f32x16& p1, const char* Ks, const bf16x8* qr, int r32, int hi, int colb0, const f32x16& negm) {
;     const char* k0 = Ks + r32 * ROWB; const char* k1 = Ks + (32 + r32) * ROWB; const int sw = (r32 & 7) << 4;
;     ...
;     const bf16x8 a0 = *reinterpret_cast<const bf16x8*>(k0 + KCB(0)), a1 = *reinterpret_cast<const bf16x8*>(k1 + KCB(0));
;     const bf16x8 c0 = *reinterpret_cast<const bf16x8*>(k0 + KCB(1)), c1 = *reinterpret_cast<const bf16x8*>(k1 + KCB(1));
;     asm volatile("s_waitcnt lgkmcnt(0)" ::: "memory"); SBAR();
;     p0 = __builtin_amdgcn_mfma_f32_32x32x16_bf16(a0, qr[0], negm, 0, 0, 0); p1 = __builtin_amdgcn_mfma_f32_32x32x16_bf16(a1, qr[0], negm, 0, 0, 0);
;     const bf16x8 e0 = *reinterpret_cast<const bf16x8*>(k0 + KCB(2)), e1 = *reinterpret_cast<const bf16x8*>(k1 + KCB(2));
;     const bf16x8 g0 = *reinterpret_cast<const bf16x8*>(k0 + KCB(3)), g1 = *reinterpret_cast<const bf16x8*>(k1 + KCB(3));
;     p0 = __builtin_amdgcn_mfma_f32_32x32x16_bf16(c0, qr[1], p0, 0, 0, 0); p1 = __builtin_amdgcn_mfma_f32_32x32x16_bf16(c1, qr[1], p1, 0, 0, 0);
;     asm volatile("s_waitcnt lgkmcnt(0)" ::: "memory"); SBAR();
;     p0 = __builtin_amdgcn_mfma_f32_32x32x16_bf16(e0, qr[2], p0, 0, 0, 0); p1 = __builtin_amdgcn_mfma_f32_32x32x16_bf16(e1, qr[2], p1, 0, 0, 0);
;     p0 = __builtin_amdgcn_mfma_f32_32x32x16_bf16(g0, qr[3], p0, 0, 0, 0); p1 = __builtin_amdgcn_mfma_f32_32x32x16_bf16(g1, qr[3], p1, 0, 0, 0);
.LBB0_281:
	v_exp_f32_e32 v10, v130
	v_exp_f32_e32 v207, v131
	v_exp_f32_e32 v212, v132
	v_exp_f32_e32 v213, v133
	v_exp_f32_e32 v214, v134
	v_exp_f32_e32 v215, v135
	v_exp_f32_e32 v216, v136
	v_exp_f32_e32 v217, v137
	v_exp_f32_e32 v218, v138
	v_exp_f32_e32 v219, v139
	v_exp_f32_e32 v220, v140
	v_exp_f32_e32 v221, v141
	v_exp_f32_e32 v222, v142
	v_exp_f32_e32 v223, v143
	v_exp_f32_e32 v224, v144
	v_exp_f32_e32 v225, v145
	v_add_u32_e32 v208, s48, v194
	v_add_u32_e32 v6, v208, v192
	v_add_u32_e32 v98, v208, v193
	ds_read_b128 v[2:5], v6
	ds_read_b128 v[6:9], v6 offset:8192
	ds_read_b128 v[12:15], v98
	ds_read_b128 v[196:199], v98 offset:8192
	v_add_u32_e32 v255, s53, v189
	ds_read_b64_tr_b16 v[236:237], v255 offset:0x0
	ds_read_b64_tr_b16 v[238:239], v255 offset:0x800
	ds_read_b64_tr_b16 v[240:241], v255 offset:0x200
	ds_read_b64_tr_b16 v[242:243], v255 offset:0xa00
	ds_read_b64_tr_b16 v[246:247], v255 offset:0x400
	ds_read_b64_tr_b16 v[248:249], v255 offset:0xc00
	ds_read_b64_tr_b16 v[250:251], v255 offset:0x600
	ds_read_b64_tr_b16 v[252:253], v255 offset:0xe00
	s_waitcnt lgkmcnt(8)
	s_waitcnt lgkmcnt(8)
	v_mfma_f32_32x32x16_bf16 v[130:145], v[2:5], v[158:161], v[82:97]
	v_mfma_f32_32x32x16_bf16 v[98:113], v[6:9], v[158:161], v[82:97]
	v_add_u32_e32 v6, v208, v190
	v_add_u32_e32 v208, v208, v195
	ds_read_b128 v[2:5], v6
	ds_read_b128 v[6:9], v6 offset:8192
	v_mfma_f32_32x32x16_bf16 v[130:145], v[12:15], v[154:157], v[130:145]
	ds_read_b128 v[12:15], v208
	ds_read_b128 v[208:211], v208 offset:8192
	s_waitcnt lgkmcnt(12)
	v_mfma_f32_32x32x16_bf16 v[98:113], v[196:199], v[154:157], v[98:113]
	s_waitcnt lgkmcnt(3)
	v_mfma_f32_32x32x16_bf16 v[130:145], v[2:5], v[150:153], v[130:145]
	v_add_f32_e32 v3, 0, v10
	v_add_f32_e32 v3, v207, v3
	v_add_f32_e32 v3, v212, v3
	v_add_f32_e32 v3, v213, v3
	v_add_f32_e32 v3, v214, v3
	v_add_f32_e32 v3, v215, v3
	v_add_f32_e32 v3, v216, v3
	v_add_f32_e32 v3, v217, v3
	v_add_f32_e32 v3, v218, v3
	v_add_f32_e32 v3, v219, v3
	v_add_f32_e32 v3, v220, v3
	v_add_f32_e32 v3, v221, v3
	v_exp_f32_e32 v2, v114
	v_add_f32_e32 v3, v222, v3
	v_exp_f32_e32 v5, v115
	v_add_f32_e32 v3, v223, v3
	v_exp_f32_e32 v115, v116
	v_add_f32_e32 v3, v224, v3
	v_exp_f32_e32 v116, v117
	v_add_f32_e32 v3, v225, v3
	v_exp_f32_e32 v117, v118
	v_add_f32_e32 v3, v2, v3
	v_exp_f32_e32 v118, v119
	v_add_f32_e32 v3, v5, v3
	s_waitcnt lgkmcnt(2)
	v_mfma_f32_32x32x16_bf16 v[98:113], v[6:9], v[150:153], v[98:113]
	v_exp_f32_e32 v119, v120
	v_add_f32_e32 v3, v115, v3
	v_exp_f32_e32 v120, v121
	v_add_f32_e32 v3, v116, v3
	v_exp_f32_e32 v121, v122
	v_add_f32_e32 v3, v117, v3
	v_exp_f32_e32 v122, v123
	v_add_f32_e32 v3, v118, v3
	v_exp_f32_e32 v123, v124
	v_add_f32_e32 v3, v119, v3
	v_exp_f32_e32 v124, v125
	v_add_f32_e32 v3, v120, v3
	v_exp_f32_e32 v125, v126
	v_add_f32_e32 v3, v121, v3
	v_exp_f32_e32 v126, v127
	v_add_f32_e32 v3, v122, v3
	s_waitcnt lgkmcnt(1)
	v_mfma_f32_32x32x16_bf16 v[130:145], v[12:15], v[146:149], v[130:145]
	v_exp_f32_e32 v127, v128
	v_add_f32_e32 v3, v123, v3
	v_exp_f32_e32 v128, v129
	v_add_f32_e32 v3, v124, v3
	v_add_f32_e32 v3, v125, v3
	v_add_f32_e32 v3, v126, v3
	v_add_f32_e32 v3, v127, v3
	s_waitcnt lgkmcnt(0)
; #define SBAR() __builtin_amdgcn_sched_barrier(0)
; #define PK8(P, BASE, OUT) do { u32x4 w = {cvtpk(P[BASE + 0], P[BASE + 1]), cvtpk(P[BASE + 2], P[BASE + 3]), cvtpk(P[BASE + 4], P[BASE + 5]), cvtpk(P[BASE + 6], P[BASE + 7])}; OUT = *reinterpret_cast<bf16x8*>(&w); } while (0)
; __device__ __forceinline__ void finishSM2T(f32x16& p0, f32x16& p1, float& l_reg, bf16x8& pa0, bf16x8& pa1, bf16x8& pa2, bf16x8& pa3) {
;     ...
;     PK8(p0, 0, pa0); PK8(p0, 8, pa1); PK8(p1, 0, pa2); PK8(p1, 8, pa3);
;     ...
; }
; template <int KS> __device__ __forceinline__ void pv_ksT(f32x16* o, int vb, bf16x8 pa) {
;     const s16x4 l0 = tr_read<v_rd_off<4>(0, KS, 0)>(vb), h0 = tr_read<v_rd_off<4>(0, KS, 1)>(vb), l1 = tr_read<v_rd_off<4>(1, KS, 0)>(vb), h1 = tr_read<v_rd_off<4>(1, KS, 1)>(vb);
;     const s16x4 l2 = tr_read<v_rd_off<4>(2, KS, 0)>(vb), h2 = tr_read<v_rd_off<4>(2, KS, 1)>(vb), l3 = tr_read<v_rd_off<4>(3, KS, 0)>(vb), h3 = tr_read<v_rd_off<4>(3, KS, 1)>(vb);
;     asm volatile("s_waitcnt lgkmcnt(0)" ::: "memory"); SBAR();
;     ...
;     o[0] = __builtin_amdgcn_mfma_f32_32x32x16_bf16(PKV(l0, h0), pa, o[0], 0, 0, 0);
;     o[1] = __builtin_amdgcn_mfma_f32_32x32x16_bf16(PKV(l1, h1), pa, o[1], 0, 0, 0);
;     o[2] = __builtin_amdgcn_mfma_f32_32x32x16_bf16(PKV(l2, h2), pa, o[2], 0, 0, 0);
;     o[3] = __builtin_amdgcn_mfma_f32_32x32x16_bf16(PKV(l3, h3), pa, o[3], 0, 0, 0);
;     ...
; }
; template <bool FIRST> __device__ __forceinline__ void partialSM2(f32x16& p0, f32x16& p1, float& m_ref, float& alpha, f32x16& negm) {
;     float pmax = p0[0];
; #pragma unroll
;     for (int r = 1; r < 16; ++r) pmax = fmaxf(pmax, p0[r]);
; #pragma unroll
;     for (int r = 0; r < 16; ++r) pmax = fmaxf(pmax, p1[r]);
;     { auto rr = __builtin_amdgcn_permlane32_swap(__float_as_uint(pmax), __float_as_uint(pmax), false, false);
;       pmax = fmaxf(__uint_as_float(rr[0]), __uint_as_float(rr[1])); }
;     alpha = 1.f;
;     if (FIRST || !__builtin_expect(__all(pmax <= ATT_THR), 1)) {
	v_mfma_f32_32x32x16_bf16 v[98:113], v[208:211], v[146:149], v[98:113]
	v_add_f32_e32 v3, v128, v3
	v_mov_b32_e32 v4, v3
	s_nop 1
	v_permlane32_swap_b32_e32 v3, v4
	v_cvt_pk_bf16_f32 v6, v10, v207
	v_cvt_pk_bf16_f32 v7, v212, v213
	v_cvt_pk_bf16_f32 v8, v214, v215
	v_cvt_pk_bf16_f32 v9, v216, v217
	v_cvt_pk_bf16_f32 v12, v218, v219
	v_cvt_pk_bf16_f32 v13, v220, v221
	v_cvt_pk_bf16_f32 v14, v222, v223
	v_cvt_pk_bf16_f32 v15, v224, v225
	v_cvt_pk_bf16_f32 v114, v2, v5
	v_cvt_pk_bf16_f32 v115, v115, v116
	v_cvt_pk_bf16_f32 v116, v117, v118
	v_cvt_pk_bf16_f32 v117, v119, v120
	v_cvt_pk_bf16_f32 v118, v121, v122
	v_cvt_pk_bf16_f32 v119, v123, v124
	v_cvt_pk_bf16_f32 v120, v125, v126
	v_cvt_pk_bf16_f32 v121, v127, v128
	ds_read_b64_tr_b16 v[212:213], v255 offset:0x1000
	ds_read_b64_tr_b16 v[214:215], v255 offset:0x1800
	ds_read_b64_tr_b16 v[216:217], v255 offset:0x1200
	ds_read_b64_tr_b16 v[218:219], v255 offset:0x1a00
	ds_read_b64_tr_b16 v[220:221], v255 offset:0x1400
	ds_read_b64_tr_b16 v[222:223], v255 offset:0x1c00
	ds_read_b64_tr_b16 v[224:225], v255 offset:0x1600
	ds_read_b64_tr_b16 v[226:227], v255 offset:0x1e00
	s_waitcnt lgkmcnt(8)
	s_nop 0
	v_mfma_f32_32x32x16_bf16 v[66:81], v[236:239], v[6:9], v[66:81]
	v_mfma_f32_32x32x16_bf16 v[50:65], v[240:243], v[6:9], v[50:65]
	v_mfma_f32_32x32x16_bf16 v[34:49], v[246:249], v[6:9], v[34:49]
	v_mfma_f32_32x32x16_bf16 v[18:33], v[250:253], v[6:9], v[18:33]
	ds_read_b64_tr_b16 v[236:237], v255 offset:0x2000
	ds_read_b64_tr_b16 v[238:239], v255 offset:0x2800
	ds_read_b64_tr_b16 v[240:241], v255 offset:0x2200
	ds_read_b64_tr_b16 v[242:243], v255 offset:0x2a00
	ds_read_b64_tr_b16 v[246:247], v255 offset:0x2400
	ds_read_b64_tr_b16 v[248:249], v255 offset:0x2c00
	ds_read_b64_tr_b16 v[250:251], v255 offset:0x2600
	ds_read_b64_tr_b16 v[252:253], v255 offset:0x2e00
	s_waitcnt lgkmcnt(8)
	s_nop 0
	v_mfma_f32_32x32x16_bf16 v[66:81], v[212:215], v[12:15], v[66:81]
	v_mfma_f32_32x32x16_bf16 v[50:65], v[216:219], v[12:15], v[50:65]
	v_mfma_f32_32x32x16_bf16 v[34:49], v[220:223], v[12:15], v[34:49]
	v_mfma_f32_32x32x16_bf16 v[18:33], v[224:227], v[12:15], v[18:33]
	ds_read_b64_tr_b16 v[212:213], v255 offset:0x3000
	ds_read_b64_tr_b16 v[214:215], v255 offset:0x3800
	ds_read_b64_tr_b16 v[216:217], v255 offset:0x3200
	ds_read_b64_tr_b16 v[218:219], v255 offset:0x3a00
	ds_read_b64_tr_b16 v[220:221], v255 offset:0x3400
	ds_read_b64_tr_b16 v[222:223], v255 offset:0x3c00
	ds_read_b64_tr_b16 v[224:225], v255 offset:0x3600
	ds_read_b64_tr_b16 v[226:227], v255 offset:0x3e00
	s_waitcnt lgkmcnt(8)
	s_nop 0
	v_mfma_f32_32x32x16_bf16 v[66:81], v[236:239], v[114:117], v[66:81]
	v_mfma_f32_32x32x16_bf16 v[50:65], v[240:243], v[114:117], v[50:65]
	v_mfma_f32_32x32x16_bf16 v[34:49], v[246:249], v[114:117], v[34:49]
	v_mfma_f32_32x32x16_bf16 v[18:33], v[250:253], v[114:117], v[18:33]
	s_waitcnt lgkmcnt(0)
	v_max_f32_e32 v2, v131, v131
	v_max_f32_e32 v5, v130, v130
	v_max_f32_e32 v2, v5, v2
	v_max3_f32 v2, v2, v132, v133
	v_max3_f32 v2, v2, v134, v135
	v_max3_f32 v2, v2, v136, v137
	v_max3_f32 v2, v2, v138, v139
	v_max3_f32 v2, v2, v140, v141
	v_max3_f32 v2, v2, v142, v143
	v_max3_f32 v2, v2, v144, v145
	v_max3_f32 v2, v2, v98, v99
	v_max3_f32 v2, v2, v100, v101
	v_max3_f32 v2, v2, v102, v103
	v_max3_f32 v2, v2, v104, v105
	v_max3_f32 v2, v2, v106, v107
	v_max3_f32 v2, v2, v108, v109
	v_mfma_f32_32x32x16_bf16 v[66:81], v[212:215], v[118:121], v[66:81]
	v_max3_f32 v2, v2, v110, v111
	v_max3_f32 v2, v2, v112, v113
	v_mov_b32_e32 v5, v2
	s_nop 1
	v_permlane32_swap_b32_e32 v2, v5
	v_max_f32_e32 v5, v5, v5
	v_max_f32_e32 v2, v2, v2
	v_mfma_f32_32x32x16_bf16 v[50:65], v[216:219], v[118:121], v[50:65]
	v_max_f32_e32 v5, v2, v5
	v_cmp_ge_f32_e32 vcc, s68, v5
	s_cmp_eq_u64 vcc, exec
	v_mov_b32_e32 v2, 1.0
	v_mfma_f32_32x32x16_bf16 v[34:49], v[220:223], v[118:121], v[34:49]
	v_mfma_f32_32x32x16_bf16 v[18:33], v[224:227], v[118:121], v[18:33]
	s_cbranch_scc0 .LBB0_298
	v_add_f32_e32 v3, v3, v4
	v_add_f32_e32 v196, v11, v3
	v_cmp_gt_f32_e32 vcc, 1.0, v2
	s_cbranch_vccz .LBB0_284
